# epilogue operand prefetch: the sample item's three gate values are requested at the start of the item instead of at its end
# speedup vs baseline: 1.0016x; 1.0016x over previous
.LBB0_2508:
	s_or_b64 exec, exec, s[0:1]
	s_ashr_i32 s85, s84, 31
	s_lshl_b64 s[0:1], s[84:85], 17
	v_and_b32_e32 v54, 15, v0
	s_add_u32 s0, s74, s0
	v_ashrrev_i32_e32 v49, 6, v0
	v_lshrrev_b32_e32 v56, 4, v17
	v_lshlrev_b32_e32 v14, 4, v54
	s_addc_u32 s1, s75, s1
	v_mov_b32_e32 v15, v1
	v_lshl_add_u64 v[52:53], s[0:1], 0, v[14:15]
	v_lshl_or_b32 v15, v49, 4, v56
	v_cmp_gt_i32_e64 s[10:11], s34, v15
	s_waitcnt vmcnt(4)
	v_add_u32_e32 v2, 0, v14
	v_add_u32_e32 v2, 0x21200, v2
	v_cndmask_b32_e64 v26, v228, v15, s[10:11]
	v_ashrrev_i32_e32 v27, 31, v26
	v_lshlrev_b64 v[28:29], 10, v[26:27]
	v_lshl_add_u64 v[30:31], v[52:53], 0, v[28:29]
	s_mul_i32 s98, s86, 0xc0
	s_mul_hi_i32 s99, s86, 0xc0
	s_add_u32 s98, s46, s98
	s_addc_u32 s99, s47, s99
	s_mul_i32 s100, s31, 48
	s_add_u32 s98, s98, s100
	s_addc_u32 s99, s99, 0
	v_lshl_add_u32 v182, v49, 1, v49
	v_ashrrev_i32_e32 v183, 31, v182
	v_lshl_add_u64 v[182:183], v[182:183], 2, s[98:99]
	global_load_dwordx3 v[184:186], v[182:183], off
	s_waitcnt lgkmcnt(0)
	s_barrier
	ds_read_b128 v[18:21], v2
	ds_read_b128 v[10:13], v2 offset:256
	ds_read_b128 v[6:9], v2 offset:512
	ds_read_b128 v[2:5], v2 offset:768
	global_load_dwordx4 v[22:25], v14, s[44:45]
	global_load_dwordx4 v[32:35], v[30:31], off
	v_lshl_add_u64 v[30:31], v[28:29], 0, s[78:79]
	v_lshl_add_u64 v[36:37], v[52:53], 0, v[30:31]
	global_load_dwordx4 v[36:39], v[36:37], off offset:256
	v_or_b32_e32 v104, 4, v15
	v_cmp_gt_i32_e64 s[98:99], s34, v104
	s_nop 1
	v_cndmask_b32_e64 v106, v228, v104, s[98:99]
	v_ashrrev_i32_e32 v107, 31, v106
	v_lshlrev_b64 v[106:107], 10, v[106:107]
	v_lshl_add_u64 v[108:109], v[52:53], 0, v[106:107]
	v_lshl_add_u64 v[106:107], v[106:107], 0, s[78:79]
	v_lshl_add_u64 v[106:107], v[52:53], 0, v[106:107]
	global_load_dwordx4 v[80:83], v[108:109], off
	global_load_dwordx4 v[84:87], v[106:107], off offset:256
	v_or_b32_e32 v110, 8, v15
	v_cmp_gt_i32_e64 s[100:101], s34, v110
	s_nop 1
	v_cndmask_b32_e64 v112, v228, v110, s[100:101]
	v_ashrrev_i32_e32 v113, 31, v112
	v_lshlrev_b64 v[112:113], 10, v[112:113]
	v_lshl_add_u64 v[114:115], v[52:53], 0, v[112:113]
	v_lshl_add_u64 v[112:113], v[112:113], 0, s[78:79]
	v_lshl_add_u64 v[112:113], v[52:53], 0, v[112:113]
	global_load_dwordx4 v[88:91], v[114:115], off
	global_load_dwordx4 v[92:95], v[112:113], off offset:256
	v_or_b32_e32 v126, 12, v15
	v_cmp_gt_i32_e64 s[98:99], s34, v126
	s_nop 1
	v_cndmask_b32_e64 v128, v228, v126, s[98:99]
	v_ashrrev_i32_e32 v129, 31, v128
	v_lshlrev_b64 v[128:129], 10, v[128:129]
	v_lshl_add_u64 v[130:131], v[52:53], 0, v[128:129]
	v_lshl_add_u64 v[128:129], v[128:129], 0, s[78:79]
	v_lshl_add_u64 v[128:129], v[52:53], 0, v[128:129]
	global_load_dwordx4 v[96:99], v[130:131], off
	global_load_dwordx4 v[100:103], v[128:129], off offset:256
	v_cmp_eq_u32_e64 s[8:9], 0, v54
	v_lshl_add_u32 v27, v15, 2, s35
	s_waitcnt vmcnt(6)
	v_pk_add_f32 v[34:35], v[34:35], v[38:39]
	v_pk_add_f32 v[36:37], v[32:33], v[36:37]
	v_pk_add_f32 v[32:33], v[24:25], v[34:35]
	v_pk_add_f32 v[34:35], v[22:23], v[36:37]
	s_waitcnt lgkmcnt(3)
	v_mul_f32_e32 v37, v21, v33
	v_mul_f32_e32 v36, v19, v35
	v_fmac_f32_e32 v36, v18, v34
	v_fmac_f32_e32 v37, v20, v32
	v_add_f32_e32 v36, v36, v37
	s_nop 1
	v_add_f32_dpp v36, v36, v36 quad_perm:[1,0,3,2] row_mask:0xf bank_mask:0xf bound_ctrl:1
	s_nop 1
	v_add_f32_dpp v36, v36, v36 quad_perm:[2,3,0,1] row_mask:0xf bank_mask:0xf bound_ctrl:1
	s_nop 1
	v_add_f32_dpp v36, v36, v36 row_half_mirror row_mask:0xf bank_mask:0xf bound_ctrl:1
	s_nop 1
	v_mov_b32_dpp v37, v36 row_mirror row_mask:0xf bank_mask:0xf bound_ctrl:1
	s_and_saveexec_b64 s[0:1], s[8:9]
	v_add_f32_e32 v36, v36, v37
	v_cndmask_b32_e64 v36, v229, v36, s[10:11]
	ds_write_b32 v27, v36
	s_or_b64 exec, exec, s[0:1]
	s_waitcnt lgkmcnt(2)
	v_mul_f32_e32 v36, v11, v35
	v_mul_f32_e32 v37, v13, v33
	v_fmac_f32_e32 v36, v10, v34
	v_fmac_f32_e32 v37, v12, v32
	v_add_f32_e32 v36, v36, v37
	s_nop 1
	v_add_f32_dpp v36, v36, v36 quad_perm:[1,0,3,2] row_mask:0xf bank_mask:0xf bound_ctrl:1
	s_nop 1
	v_add_f32_dpp v36, v36, v36 quad_perm:[2,3,0,1] row_mask:0xf bank_mask:0xf bound_ctrl:1
	s_nop 1
	v_add_f32_dpp v36, v36, v36 row_half_mirror row_mask:0xf bank_mask:0xf bound_ctrl:1
	s_nop 1
	v_mov_b32_dpp v37, v36 row_mirror row_mask:0xf bank_mask:0xf bound_ctrl:1
	s_and_saveexec_b64 s[0:1], s[8:9]
	v_add_f32_e32 v36, v36, v37
	v_cndmask_b32_e64 v36, v229, v36, s[10:11]
	ds_write_b32 v27, v36 offset:512
	s_or_b64 exec, exec, s[0:1]
	s_waitcnt lgkmcnt(1)
	v_mul_f32_e32 v36, v7, v35
	v_mul_f32_e32 v37, v9, v33
	v_fmac_f32_e32 v36, v6, v34
	v_fmac_f32_e32 v37, v8, v32
	v_add_f32_e32 v36, v36, v37
	s_nop 1
	v_add_f32_dpp v36, v36, v36 quad_perm:[1,0,3,2] row_mask:0xf bank_mask:0xf bound_ctrl:1
	s_nop 1
	v_add_f32_dpp v36, v36, v36 quad_perm:[2,3,0,1] row_mask:0xf bank_mask:0xf bound_ctrl:1
	s_nop 1
	v_add_f32_dpp v36, v36, v36 row_half_mirror row_mask:0xf bank_mask:0xf bound_ctrl:1
	s_nop 1
	v_mov_b32_dpp v37, v36 row_mirror row_mask:0xf bank_mask:0xf bound_ctrl:1
	s_and_saveexec_b64 s[0:1], s[8:9]
	v_add_f32_e32 v36, v36, v37
	v_cndmask_b32_e64 v36, v229, v36, s[10:11]
	ds_write_b32 v27, v36 offset:1024
	s_or_b64 exec, exec, s[0:1]
	s_waitcnt lgkmcnt(0)
	v_mul_f32_e32 v35, v3, v35
	v_mul_f32_e32 v33, v5, v33
	v_fmac_f32_e32 v35, v2, v34
	v_fmac_f32_e32 v33, v4, v32
	v_add_f32_e32 v32, v35, v33
	s_nop 1
	v_add_f32_dpp v32, v32, v32 quad_perm:[1,0,3,2] row_mask:0xf bank_mask:0xf bound_ctrl:1
	s_nop 1
	v_add_f32_dpp v32, v32, v32 quad_perm:[2,3,0,1] row_mask:0xf bank_mask:0xf bound_ctrl:1
	s_nop 1
	v_add_f32_dpp v32, v32, v32 row_half_mirror row_mask:0xf bank_mask:0xf bound_ctrl:1
	s_nop 1
	v_mov_b32_dpp v33, v32 row_mirror row_mask:0xf bank_mask:0xf bound_ctrl:1
	s_and_saveexec_b64 s[0:1], s[8:9]
	v_add_f32_e32 v32, v32, v33
	v_cndmask_b32_e64 v32, v229, v32, s[10:11]
	ds_write_b32 v27, v32 offset:1536
	s_or_b64 exec, exec, s[0:1]
	v_or_b32_e32 v27, 4, v15
	v_cmp_gt_i32_e64 s[12:13], s34, v27
	s_nop 1
	v_cndmask_b32_e64 v32, v228, v27, s[12:13]
	v_ashrrev_i32_e32 v33, 31, v32
	v_lshlrev_b64 v[34:35], 10, v[32:33]
	v_lshl_add_u64 v[36:37], v[34:35], 0, s[78:79]
	v_lshl_add_u64 v[38:39], v[52:53], 0, v[34:35]
	v_lshl_add_u64 v[42:43], v[52:53], 0, v[36:37]
	v_lshl_add_u32 v27, v27, 2, s35
	s_waitcnt vmcnt(4)
	v_mov_b64 v[38:39], v[80:81]
	v_mov_b64 v[40:41], v[82:83]
	v_mov_b64 v[42:43], v[84:85]
	v_mov_b64 v[44:45], v[86:87]
	v_pk_add_f32 v[40:41], v[40:41], v[44:45]
	v_pk_add_f32 v[42:43], v[38:39], v[42:43]
	v_pk_add_f32 v[38:39], v[24:25], v[40:41]
	v_pk_add_f32 v[40:41], v[22:23], v[42:43]
	v_mul_f32_e32 v42, v21, v39
	v_mul_f32_e32 v33, v19, v41
	v_fmac_f32_e32 v33, v18, v40
	v_fmac_f32_e32 v42, v20, v38
	v_add_f32_e32 v33, v33, v42
	s_nop 1
	v_add_f32_dpp v33, v33, v33 quad_perm:[1,0,3,2] row_mask:0xf bank_mask:0xf bound_ctrl:1
	s_nop 1
	v_add_f32_dpp v33, v33, v33 quad_perm:[2,3,0,1] row_mask:0xf bank_mask:0xf bound_ctrl:1
	s_nop 1
	v_add_f32_dpp v33, v33, v33 row_half_mirror row_mask:0xf bank_mask:0xf bound_ctrl:1
	s_nop 1
	v_mov_b32_dpp v42, v33 row_mirror row_mask:0xf bank_mask:0xf bound_ctrl:1
	s_and_saveexec_b64 s[0:1], s[8:9]
	v_add_f32_e32 v33, v33, v42
	v_cndmask_b32_e64 v33, v229, v33, s[12:13]
	ds_write_b32 v27, v33
	s_or_b64 exec, exec, s[0:1]
	v_mul_f32_e32 v33, v11, v41
	v_mul_f32_e32 v42, v13, v39
	v_fmac_f32_e32 v33, v10, v40
	v_fmac_f32_e32 v42, v12, v38
	v_add_f32_e32 v33, v33, v42
	s_nop 1
	v_add_f32_dpp v33, v33, v33 quad_perm:[1,0,3,2] row_mask:0xf bank_mask:0xf bound_ctrl:1
	s_nop 1
	v_add_f32_dpp v33, v33, v33 quad_perm:[2,3,0,1] row_mask:0xf bank_mask:0xf bound_ctrl:1
	s_nop 1
	v_add_f32_dpp v33, v33, v33 row_half_mirror row_mask:0xf bank_mask:0xf bound_ctrl:1
	s_nop 1
	v_mov_b32_dpp v42, v33 row_mirror row_mask:0xf bank_mask:0xf bound_ctrl:1
	s_and_saveexec_b64 s[0:1], s[8:9]
	v_add_f32_e32 v33, v33, v42
	v_cndmask_b32_e64 v33, v229, v33, s[12:13]
	ds_write_b32 v27, v33 offset:512
	s_or_b64 exec, exec, s[0:1]
	v_mul_f32_e32 v33, v7, v41
	v_mul_f32_e32 v42, v9, v39
	v_fmac_f32_e32 v33, v6, v40
	v_fmac_f32_e32 v42, v8, v38
	v_add_f32_e32 v33, v33, v42
	s_nop 1
	v_add_f32_dpp v33, v33, v33 quad_perm:[1,0,3,2] row_mask:0xf bank_mask:0xf bound_ctrl:1
	s_nop 1
	v_add_f32_dpp v33, v33, v33 quad_perm:[2,3,0,1] row_mask:0xf bank_mask:0xf bound_ctrl:1
	s_nop 1
	v_add_f32_dpp v33, v33, v33 row_half_mirror row_mask:0xf bank_mask:0xf bound_ctrl:1
	s_nop 1
	v_mov_b32_dpp v42, v33 row_mirror row_mask:0xf bank_mask:0xf bound_ctrl:1
	s_and_saveexec_b64 s[0:1], s[8:9]
	v_add_f32_e32 v33, v33, v42
	v_cndmask_b32_e64 v33, v229, v33, s[12:13]
	ds_write_b32 v27, v33 offset:1024
	s_or_b64 exec, exec, s[0:1]
	v_mul_f32_e32 v33, v3, v41
	v_mul_f32_e32 v39, v5, v39
	v_fmac_f32_e32 v33, v2, v40
	v_fmac_f32_e32 v39, v4, v38
	v_add_f32_e32 v33, v33, v39
	s_nop 1
	v_add_f32_dpp v33, v33, v33 quad_perm:[1,0,3,2] row_mask:0xf bank_mask:0xf bound_ctrl:1
	s_nop 1
	v_add_f32_dpp v33, v33, v33 quad_perm:[2,3,0,1] row_mask:0xf bank_mask:0xf bound_ctrl:1
	s_nop 1
	v_add_f32_dpp v33, v33, v33 row_half_mirror row_mask:0xf bank_mask:0xf bound_ctrl:1
	s_nop 1
	v_mov_b32_dpp v38, v33 row_mirror row_mask:0xf bank_mask:0xf bound_ctrl:1
	s_and_saveexec_b64 s[0:1], s[8:9]
	v_add_f32_e32 v33, v33, v38
	v_cndmask_b32_e64 v33, v229, v33, s[12:13]
	ds_write_b32 v27, v33 offset:1536
	s_or_b64 exec, exec, s[0:1]
	v_or_b32_e32 v27, 8, v15
	v_cmp_gt_i32_e64 s[16:17], s34, v27
	s_nop 1
	v_cndmask_b32_e64 v38, v228, v27, s[16:17]
	v_ashrrev_i32_e32 v39, 31, v38
	v_lshlrev_b64 v[40:41], 10, v[38:39]
	v_lshl_add_u64 v[44:45], v[52:53], 0, v[40:41]
	v_lshl_add_u64 v[42:43], v[40:41], 0, s[78:79]
	v_lshl_add_u64 v[50:51], v[52:53], 0, v[42:43]
	v_lshl_add_u32 v27, v27, 2, s35
	s_waitcnt vmcnt(2)
	v_mov_b64 v[44:45], v[88:89]
	v_mov_b64 v[46:47], v[90:91]
	v_mov_b64 v[58:59], v[92:93]
	v_mov_b64 v[60:61], v[94:95]
	v_pk_add_f32 v[46:47], v[46:47], v[60:61]
	v_pk_add_f32 v[50:51], v[44:45], v[58:59]
	v_pk_add_f32 v[44:45], v[24:25], v[46:47]
	v_pk_add_f32 v[46:47], v[22:23], v[50:51]
	v_mul_f32_e32 v39, v21, v45
	v_mul_f32_e32 v33, v19, v47
	v_fmac_f32_e32 v33, v18, v46
	v_fmac_f32_e32 v39, v20, v44
	v_add_f32_e32 v33, v33, v39
	s_nop 1
	v_add_f32_dpp v33, v33, v33 quad_perm:[1,0,3,2] row_mask:0xf bank_mask:0xf bound_ctrl:1
	s_nop 1
	v_add_f32_dpp v33, v33, v33 quad_perm:[2,3,0,1] row_mask:0xf bank_mask:0xf bound_ctrl:1
	s_nop 1
	v_add_f32_dpp v33, v33, v33 row_half_mirror row_mask:0xf bank_mask:0xf bound_ctrl:1
	s_nop 1
	v_mov_b32_dpp v39, v33 row_mirror row_mask:0xf bank_mask:0xf bound_ctrl:1
	s_and_saveexec_b64 s[0:1], s[8:9]
	v_add_f32_e32 v33, v33, v39
	v_cndmask_b32_e64 v33, v229, v33, s[16:17]
	ds_write_b32 v27, v33
	s_or_b64 exec, exec, s[0:1]
	v_mul_f32_e32 v33, v11, v47
	v_mul_f32_e32 v39, v13, v45
	v_fmac_f32_e32 v33, v10, v46
	v_fmac_f32_e32 v39, v12, v44
	v_add_f32_e32 v33, v33, v39
	s_nop 1
	v_add_f32_dpp v33, v33, v33 quad_perm:[1,0,3,2] row_mask:0xf bank_mask:0xf bound_ctrl:1
	s_nop 1
	v_add_f32_dpp v33, v33, v33 quad_perm:[2,3,0,1] row_mask:0xf bank_mask:0xf bound_ctrl:1
	s_nop 1
	v_add_f32_dpp v33, v33, v33 row_half_mirror row_mask:0xf bank_mask:0xf bound_ctrl:1
	s_nop 1
	v_mov_b32_dpp v39, v33 row_mirror row_mask:0xf bank_mask:0xf bound_ctrl:1
	s_and_saveexec_b64 s[0:1], s[8:9]
	v_add_f32_e32 v33, v33, v39
	v_cndmask_b32_e64 v33, v229, v33, s[16:17]
	ds_write_b32 v27, v33 offset:512
	s_or_b64 exec, exec, s[0:1]
	v_mul_f32_e32 v33, v7, v47
	v_mul_f32_e32 v39, v9, v45
	v_fmac_f32_e32 v33, v6, v46
	v_fmac_f32_e32 v39, v8, v44
	v_add_f32_e32 v33, v33, v39
	s_nop 1
	v_add_f32_dpp v33, v33, v33 quad_perm:[1,0,3,2] row_mask:0xf bank_mask:0xf bound_ctrl:1
	s_nop 1
	v_add_f32_dpp v33, v33, v33 quad_perm:[2,3,0,1] row_mask:0xf bank_mask:0xf bound_ctrl:1
	s_nop 1
	v_add_f32_dpp v33, v33, v33 row_half_mirror row_mask:0xf bank_mask:0xf bound_ctrl:1
	s_nop 1
	v_mov_b32_dpp v39, v33 row_mirror row_mask:0xf bank_mask:0xf bound_ctrl:1
	s_and_saveexec_b64 s[0:1], s[8:9]
	v_add_f32_e32 v33, v33, v39
	v_cndmask_b32_e64 v33, v229, v33, s[16:17]
	ds_write_b32 v27, v33 offset:1024
	s_or_b64 exec, exec, s[0:1]
	v_mul_f32_e32 v33, v3, v47
	v_mul_f32_e32 v39, v5, v45
	v_fmac_f32_e32 v33, v2, v46
	v_fmac_f32_e32 v39, v4, v44
	v_add_f32_e32 v33, v33, v39
	s_nop 1
	v_add_f32_dpp v33, v33, v33 quad_perm:[1,0,3,2] row_mask:0xf bank_mask:0xf bound_ctrl:1
	s_nop 1
	v_add_f32_dpp v33, v33, v33 quad_perm:[2,3,0,1] row_mask:0xf bank_mask:0xf bound_ctrl:1
	s_nop 1
	v_add_f32_dpp v33, v33, v33 row_half_mirror row_mask:0xf bank_mask:0xf bound_ctrl:1
	s_nop 1
	v_mov_b32_dpp v39, v33 row_mirror row_mask:0xf bank_mask:0xf bound_ctrl:1
	s_and_saveexec_b64 s[0:1], s[8:9]
	v_add_f32_e32 v33, v33, v39
	v_cndmask_b32_e64 v33, v229, v33, s[16:17]
	ds_write_b32 v27, v33 offset:1536
	s_or_b64 exec, exec, s[0:1]
	v_or_b32_e32 v15, 12, v15
	v_cmp_gt_i32_e64 s[18:19], s34, v15
	s_nop 1
	v_cndmask_b32_e64 v44, v228, v15, s[18:19]
	v_ashrrev_i32_e32 v45, 31, v44
	v_lshlrev_b64 v[46:47], 10, v[44:45]
	v_lshl_add_u64 v[58:59], v[52:53], 0, v[46:47]
	v_lshl_add_u64 v[50:51], v[46:47], 0, s[78:79]
	v_lshl_add_u64 v[52:53], v[52:53], 0, v[50:51]
	v_lshl_add_u32 v15, v15, 2, s35
	s_waitcnt vmcnt(0)
	v_mov_b64 v[58:59], v[96:97]
	v_mov_b64 v[60:61], v[98:99]
	v_mov_b64 v[62:63], v[100:101]
	v_mov_b64 v[64:65], v[102:103]
	v_pk_add_f32 v[52:53], v[60:61], v[64:65]
	v_pk_add_f32 v[58:59], v[58:59], v[62:63]
	v_pk_add_f32 v[24:25], v[24:25], v[52:53]
	v_pk_add_f32 v[22:23], v[22:23], v[58:59]
	v_mul_f32_e32 v21, v21, v25
	v_mul_f32_e32 v19, v19, v23
	v_fmac_f32_e32 v19, v18, v22
	v_fmac_f32_e32 v21, v20, v24
	v_add_f32_e32 v18, v19, v21
	s_nop 1
	v_add_f32_dpp v18, v18, v18 quad_perm:[1,0,3,2] row_mask:0xf bank_mask:0xf bound_ctrl:1
	s_nop 1
	v_add_f32_dpp v18, v18, v18 quad_perm:[2,3,0,1] row_mask:0xf bank_mask:0xf bound_ctrl:1
	s_nop 1
	v_add_f32_dpp v18, v18, v18 row_half_mirror row_mask:0xf bank_mask:0xf bound_ctrl:1
	s_nop 1
	v_mov_b32_dpp v19, v18 row_mirror row_mask:0xf bank_mask:0xf bound_ctrl:1
	s_and_saveexec_b64 s[0:1], s[8:9]
	v_add_f32_e32 v18, v18, v19
	v_cndmask_b32_e64 v18, v229, v18, s[18:19]
	ds_write_b32 v15, v18
	s_or_b64 exec, exec, s[0:1]
	v_mul_f32_e32 v11, v11, v23
	v_fmac_f32_e32 v11, v10, v22
	v_mul_f32_e32 v10, v13, v25
	v_fmac_f32_e32 v10, v12, v24
	v_add_f32_e32 v10, v11, v10
	s_nop 1
	v_add_f32_dpp v10, v10, v10 quad_perm:[1,0,3,2] row_mask:0xf bank_mask:0xf bound_ctrl:1
	s_nop 1
	v_add_f32_dpp v10, v10, v10 quad_perm:[2,3,0,1] row_mask:0xf bank_mask:0xf bound_ctrl:1
	s_nop 1
	v_add_f32_dpp v10, v10, v10 row_half_mirror row_mask:0xf bank_mask:0xf bound_ctrl:1
	s_nop 1
	v_mov_b32_dpp v11, v10 row_mirror row_mask:0xf bank_mask:0xf bound_ctrl:1
	s_and_saveexec_b64 s[0:1], s[8:9]
	v_add_f32_e32 v10, v10, v11
	v_cndmask_b32_e64 v10, v229, v10, s[18:19]
	ds_write_b32 v15, v10 offset:512
	s_or_b64 exec, exec, s[0:1]
	v_mul_f32_e32 v7, v7, v23
	v_fmac_f32_e32 v7, v6, v22
	v_mul_f32_e32 v6, v9, v25
	v_fmac_f32_e32 v6, v8, v24
	v_add_f32_e32 v6, v7, v6
	s_nop 1
	v_add_f32_dpp v6, v6, v6 quad_perm:[1,0,3,2] row_mask:0xf bank_mask:0xf bound_ctrl:1
	s_nop 1
	v_add_f32_dpp v6, v6, v6 quad_perm:[2,3,0,1] row_mask:0xf bank_mask:0xf bound_ctrl:1
	s_nop 1
	v_add_f32_dpp v6, v6, v6 row_half_mirror row_mask:0xf bank_mask:0xf bound_ctrl:1
	s_nop 1
	v_mov_b32_dpp v7, v6 row_mirror row_mask:0xf bank_mask:0xf bound_ctrl:1
	s_and_saveexec_b64 s[0:1], s[8:9]
	v_add_f32_e32 v6, v6, v7
	v_cndmask_b32_e64 v6, v229, v6, s[18:19]
	ds_write_b32 v15, v6 offset:1024
	s_or_b64 exec, exec, s[0:1]
	v_mul_f32_e32 v3, v3, v23
	v_fmac_f32_e32 v3, v2, v22
	v_mul_f32_e32 v2, v5, v25
	v_fmac_f32_e32 v2, v4, v24
	v_add_f32_e32 v2, v3, v2
	s_nop 1
	v_add_f32_dpp v2, v2, v2 quad_perm:[1,0,3,2] row_mask:0xf bank_mask:0xf bound_ctrl:1
	s_nop 1
	v_add_f32_dpp v2, v2, v2 quad_perm:[2,3,0,1] row_mask:0xf bank_mask:0xf bound_ctrl:1
	s_nop 1
	v_add_f32_dpp v2, v2, v2 row_half_mirror row_mask:0xf bank_mask:0xf bound_ctrl:1
	s_nop 1
	v_mov_b32_dpp v3, v2 row_mirror row_mask:0xf bank_mask:0xf bound_ctrl:1
	s_and_saveexec_b64 s[0:1], s[8:9]
	v_add_f32_e32 v2, v2, v3
	v_cndmask_b32_e64 v2, v229, v2, s[18:19]
	ds_write_b32 v15, v2 offset:1536
	s_or_b64 exec, exec, s[0:1]
	v_cmp_gt_i32_e32 vcc, 4, v49
	v_lshlrev_b32_e32 v45, 2, v17
	s_waitcnt lgkmcnt(0)
	s_barrier
	s_and_saveexec_b64 s[0:1], vcc
	s_cbranch_execz .LBB0_2542
	v_lshlrev_b32_e32 v2, 9, v49
	v_add3_u32 v4, s35, v2, v45
	ds_read2st64_b32 v[2:3], v4 offset1:1
	s_waitcnt lgkmcnt(0)
	v_max_f32_e32 v5, v3, v3
	v_max_f32_e32 v6, v2, v2
	v_max_f32_e32 v5, v6, v5
	v_cmp_lt_f32_e32 vcc, s2, v2
	s_nop 0
	v_mov_b32_dpp v6, v5 quad_perm:[1,0,3,2] row_mask:0xf bank_mask:0xf bound_ctrl:1
	v_max_f32_e32 v6, v6, v6
	v_max_f32_e32 v5, v5, v6
	s_nop 1
	v_mov_b32_dpp v6, v5 quad_perm:[2,3,0,1] row_mask:0xf bank_mask:0xf bound_ctrl:1
	v_max_f32_e32 v6, v6, v6
	v_max_f32_e32 v5, v5, v6
	s_nop 1
	v_mov_b32_dpp v6, v5 row_half_mirror row_mask:0xf bank_mask:0xf bound_ctrl:1
	v_max_f32_e32 v6, v6, v6
	v_max_f32_e32 v5, v5, v6
	s_nop 1
	v_mov_b32_dpp v6, v5 row_mirror row_mask:0xf bank_mask:0xf bound_ctrl:1
	v_max_f32_e32 v6, v6, v6
	v_max_f32_e32 v5, v5, v6
	ds_swizzle_b32 v6, v5 offset:swizzle(SWAP,16)
	s_waitcnt lgkmcnt(0)
	v_max_f32_e32 v6, v6, v6
	v_max_f32_e32 v5, v5, v6
	v_mov_b32_e32 v6, v5
	s_nop 1
	v_permlane32_swap_b32_e32 v5, v6
	v_max_f32_e32 v6, v6, v6
	v_max_f32_e32 v5, v5, v5
	v_max_f32_e32 v5, v5, v6
	v_sub_f32_e32 v6, v2, v5
	v_exp_f32_e32 v6, v6
	v_sub_f32_e32 v5, v3, v5
	v_exp_f32_e32 v5, v5
	v_cndmask_b32_e32 v2, 0, v6, vcc
	v_cmp_lt_f32_e32 vcc, s2, v3
	s_nop 1
	v_cndmask_b32_e32 v3, 0, v5, vcc
	v_add_f32_e32 v5, v2, v3
	s_nop 1
	v_add_f32_dpp v5, v5, v5 quad_perm:[1,0,3,2] row_mask:0xf bank_mask:0xf bound_ctrl:1
	s_nop 1
	v_add_f32_dpp v5, v5, v5 quad_perm:[2,3,0,1] row_mask:0xf bank_mask:0xf bound_ctrl:1
	s_nop 1
	v_add_f32_dpp v5, v5, v5 row_half_mirror row_mask:0xf bank_mask:0xf bound_ctrl:1
	s_nop 1
	v_add_f32_dpp v5, v5, v5 row_mirror row_mask:0xf bank_mask:0xf bound_ctrl:1
	ds_swizzle_b32 v6, v5 offset:swizzle(SWAP,16)
	s_waitcnt lgkmcnt(0)
	v_add_f32_e32 v5, v5, v6
	v_mov_b32_e32 v6, v5
	s_nop 1
	v_permlane32_swap_b32_e32 v5, v6
	v_add_f32_e32 v5, v5, v6
	v_div_scale_f32 v6, s[20:21], v5, v5, 1.0
	v_rcp_f32_e32 v7, v6
	v_div_scale_f32 v8, vcc, 1.0, v5, 1.0
	v_fma_f32 v9, -v6, v7, 1.0
	v_fmac_f32_e32 v7, v9, v7
	v_mul_f32_e32 v9, v8, v7
	v_fma_f32 v10, -v6, v9, v8
	v_fmac_f32_e32 v9, v10, v7
	v_fma_f32 v6, -v6, v9, v8
	v_div_fmas_f32 v6, v6, v7, v9
	v_div_fixup_f32 v6, v6, v5, 1.0
	v_cmp_lt_f32_e32 vcc, 0, v5
	s_nop 1
	v_cndmask_b32_e32 v5, 0, v6, vcc
	v_mul_f32_e32 v2, v2, v5
	v_mul_f32_e32 v3, v3, v5
	ds_write2st64_b32 v4, v2, v3 offset1:1

.LBB0_2656:
	s_or_b64 exec, exec, s[0:1]
	s_barrier
	s_and_saveexec_b64 s[0:1], s[6:7]
	s_cbranch_execz .LBB0_2499
	s_mul_i32 s7, s86, 0xc0
	s_mul_hi_i32 s6, s86, 0xc0
	s_add_u32 s7, s46, s7
	s_addc_u32 s8, s47, s6
	s_mul_i32 s31, s31, 48
	s_add_u32 s6, s7, s31
	v_lshl_add_u32 v2, v49, 1, v49
	s_addc_u32 s7, s8, 0
	v_ashrrev_i32_e32 v3, 31, v2
	v_lshl_add_u64 v[2:3], v[2:3], 2, s[6:7]
	s_lshl_b64 s[6:7], s[86:87], 11
	s_add_u32 s6, s52, s6
	v_ashrrev_i32_e32 v49, 31, v48
	s_addc_u32 s7, s53, s7
	s_waitcnt vmcnt(0)
	v_mov_b32_e32 v6, v184
	v_mov_b32_e32 v7, v185
	v_mov_b32_e32 v8, v186
	v_mov_b32_e32 v2, v7
	v_mov_b32_e32 v3, v8
	v_pk_mul_f32 v[2:3], v[4:5], v[2:3]
	s_nop 0
	v_fma_f32 v0, v106, v6, v2
	v_add_f32_e32 v0, v0, v3
	v_cvt_pk_bf16_f32 v4, v0, s0
	v_lshl_add_u64 v[2:3], v[48:49], 1, s[6:7]
	v_lshlrev_b32_e32 v0, 1, v17
	v_lshl_add_u64 v[2:3], v[2:3], 0, v[0:1]
	global_store_short v[2:3], v4, off
	s_branch .LBB0_2499
